# v14 plus lru_in GEMM loop: second-half A-fragment LDS reads hoisted before the first MFMA batch
# speedup vs baseline: 1.0003x; 1.0003x over previous
.LBB0_712:
	s_waitcnt vmcnt(5)
	ds_write_b128 v156, v[112:115]
	s_waitcnt vmcnt(4)
	ds_write_b128 v156, v[116:119] offset:6144
	s_waitcnt vmcnt(3)
	ds_write_b128 v156, v[120:123] offset:12288
	s_waitcnt vmcnt(2)
	ds_write_b128 v156, v[124:127] offset:18432
	s_waitcnt vmcnt(1)
	ds_write_b128 v156, v[136:139] offset:24576
	s_waitcnt vmcnt(0)
	ds_write_b128 v156, v[140:143] offset:30720
	v_lshl_add_u64 v[116:117], v[162:163], 0, s[0:1]
	v_add_co_u32_e32 v124, vcc, s69, v116
	s_waitcnt lgkmcnt(0)
	s_barrier
	ds_read_b128 v[112:115], v168 offset:12288
	ds_read_b128 v[120:123], v168 offset:13824
	ds_read_b128 v[172:175], v167
	ds_read_b128 v[176:179], v167 offset:1536
	ds_read_b128 v[140:143], v168 offset:15360
	ds_read_b128 v[180:183], v168 offset:16896
	v_lshl_add_u64 v[118:119], v[164:165], 0, s[0:1]
	v_addc_co_u32_e32 v125, vcc, 0, v117, vcc
	v_add_co_u32_e32 v126, vcc, s78, v118
	ds_read_b128 v[184:187], v167 offset:3072
	ds_read_b128 v[200:203], v167 offset:4608
	ds_read_b128 v[216:219], v168 offset:18432
	ds_read_b128 v[220:223], v168 offset:19968
	ds_read_b128 v[224:227], v168 offset:21504
	ds_read_b128 v[228:231], v168 offset:23040
	v_addc_co_u32_e32 v127, vcc, 0, v119, vcc
	v_add_co_u32_e32 v136, vcc, s79, v118
	s_waitcnt lgkmcnt(9)
	v_mfma_f32_16x16x32_bf16 v[148:151], v[112:115], v[172:175], v[148:151]
	v_addc_co_u32_e32 v137, vcc, 0, v119, vcc
	v_add_co_u32_e32 v138, vcc, s80, v118
	v_mfma_f32_16x16x32_bf16 v[144:147], v[120:123], v[172:175], v[144:147]
	s_nop 0
	v_addc_co_u32_e32 v139, vcc, 0, v119, vcc
	v_add_co_u32_e32 v204, vcc, s81, v118
	s_waitcnt lgkmcnt(8)
	v_mfma_f32_16x16x32_bf16 v[108:111], v[112:115], v[176:179], v[108:111]
	v_addc_co_u32_e32 v205, vcc, 0, v119, vcc
	v_mfma_f32_16x16x32_bf16 v[100:103], v[120:123], v[176:179], v[100:103]
	s_waitcnt lgkmcnt(5)
	v_mfma_f32_16x16x32_bf16 v[60:63], v[112:115], v[184:187], v[60:63]
	v_mfma_f32_16x16x32_bf16 v[56:59], v[120:123], v[184:187], v[56:59]
	s_waitcnt lgkmcnt(4)
	v_mfma_f32_16x16x32_bf16 v[28:31], v[112:115], v[200:203], v[28:31]
	global_load_dwordx4 v[112:115], v[116:117], off offset:64
	s_nop 0
	global_load_dwordx4 v[116:119], v[124:125], off offset:64
	v_mfma_f32_16x16x32_bf16 v[24:27], v[120:123], v[200:203], v[24:27]
	global_load_dwordx4 v[120:123], v[126:127], off offset:64
	s_nop 0
	global_load_dwordx4 v[124:127], v[136:137], off offset:64
	s_nop 0
	global_load_dwordx4 v[136:139], v[138:139], off offset:64
	v_mfma_f32_16x16x32_bf16 v[132:135], v[140:143], v[172:175], v[132:135]
	v_mfma_f32_16x16x32_bf16 v[84:87], v[140:143], v[176:179], v[84:87]
	v_mfma_f32_16x16x32_bf16 v[52:55], v[140:143], v[184:187], v[52:55]
	v_mfma_f32_16x16x32_bf16 v[20:23], v[140:143], v[200:203], v[20:23]
	global_load_dwordx4 v[140:143], v[204:205], off offset:64
	v_mfma_f32_16x16x32_bf16 v[128:131], v[180:183], v[172:175], v[128:131]
	v_mfma_f32_16x16x32_bf16 v[80:83], v[180:183], v[176:179], v[80:83]
	v_mfma_f32_16x16x32_bf16 v[48:51], v[180:183], v[184:187], v[48:51]
	v_mfma_f32_16x16x32_bf16 v[16:19], v[180:183], v[200:203], v[16:19]
	s_waitcnt lgkmcnt(3)
	v_mfma_f32_16x16x32_bf16 v[104:107], v[216:219], v[172:175], v[104:107]
	s_waitcnt lgkmcnt(2)
	v_mfma_f32_16x16x32_bf16 v[96:99], v[220:223], v[172:175], v[96:99]
	s_waitcnt lgkmcnt(1)
	v_mfma_f32_16x16x32_bf16 v[92:95], v[224:227], v[172:175], v[92:95]
	s_waitcnt lgkmcnt(0)
	v_mfma_f32_16x16x32_bf16 v[88:91], v[228:231], v[172:175], v[88:91]
	v_mfma_f32_16x16x32_bf16 v[76:79], v[216:219], v[176:179], v[76:79]
	v_mfma_f32_16x16x32_bf16 v[72:75], v[220:223], v[176:179], v[72:75]
	v_mfma_f32_16x16x32_bf16 v[68:71], v[224:227], v[176:179], v[68:71]
	v_mfma_f32_16x16x32_bf16 v[64:67], v[228:231], v[176:179], v[64:67]
	v_mfma_f32_16x16x32_bf16 v[44:47], v[216:219], v[184:187], v[44:47]
	v_mfma_f32_16x16x32_bf16 v[40:43], v[220:223], v[184:187], v[40:43]
	v_mfma_f32_16x16x32_bf16 v[36:39], v[224:227], v[184:187], v[36:39]
	v_mfma_f32_16x16x32_bf16 v[32:35], v[228:231], v[184:187], v[32:35]
	v_mfma_f32_16x16x32_bf16 v[12:15], v[216:219], v[200:203], v[12:15]
	v_mfma_f32_16x16x32_bf16 v[8:11], v[220:223], v[200:203], v[8:11]
	v_mfma_f32_16x16x32_bf16 v[4:7], v[224:227], v[200:203], v[4:7]
	v_mfma_f32_16x16x32_bf16 v[0:3], v[228:231], v[200:203], v[0:3]
	s_add_u32 s0, s0, 64
	s_addc_u32 s1, s1, 0
	s_cmpk_lg_i32 s0, 0xfc0
	s_barrier
	s_cbranch_scc1 .LBB0_712
	s_waitcnt vmcnt(5)
	ds_write_b128 v156, v[112:115]
	s_waitcnt vmcnt(4)
	ds_write_b128 v156, v[116:119] offset:6144
	s_waitcnt vmcnt(3)
	ds_write_b128 v156, v[120:123] offset:12288
	s_waitcnt vmcnt(2)
	ds_write_b128 v156, v[124:127] offset:18432
	s_waitcnt vmcnt(1)
	ds_write_b128 v156, v[136:139] offset:24576
	s_waitcnt vmcnt(0)
	ds_write_b128 v156, v[140:143] offset:30720
	s_waitcnt lgkmcnt(0)
	s_barrier
	ds_read_b128 v[136:139], v168 offset:12288
	ds_read_b128 v[140:143], v168 offset:13824
	ds_read_b128 v[162:165], v167
	ds_read_b128 v[172:175], v167 offset:1536
	s_waitcnt lgkmcnt(1)
	v_mfma_f32_16x16x32_bf16 v[124:127], v[136:139], v[162:165], v[148:151]
	s_nop 2
	ds_read_b128 v[148:151], v168 offset:15360
	v_mfma_f32_16x16x32_bf16 v[120:123], v[140:143], v[162:165], v[144:147]
	s_nop 2
	ds_read_b128 v[144:147], v168 offset:16896
	s_waitcnt lgkmcnt(1)
	v_mfma_f32_16x16x32_bf16 v[116:119], v[148:151], v[162:165], v[132:135]
	s_waitcnt lgkmcnt(0)
	v_mfma_f32_16x16x32_bf16 v[112:115], v[144:147], v[162:165], v[128:131]
	s_nop 2
	ds_read_b128 v[128:131], v167 offset:3072
	ds_read_b128 v[132:135], v167 offset:4608
	v_mfma_f32_16x16x32_bf16 v[108:111], v[136:139], v[172:175], v[108:111]
	v_mfma_f32_16x16x32_bf16 v[100:103], v[140:143], v[172:175], v[100:103]
	v_mfma_f32_16x16x32_bf16 v[84:87], v[148:151], v[172:175], v[84:87]
	v_mfma_f32_16x16x32_bf16 v[80:83], v[144:147], v[172:175], v[80:83]
	s_waitcnt lgkmcnt(1)
	v_mfma_f32_16x16x32_bf16 v[60:63], v[136:139], v[128:131], v[60:63]
	v_mfma_f32_16x16x32_bf16 v[56:59], v[140:143], v[128:131], v[56:59]
	v_mfma_f32_16x16x32_bf16 v[52:55], v[148:151], v[128:131], v[52:55]
	v_mfma_f32_16x16x32_bf16 v[48:51], v[144:147], v[128:131], v[48:51]
	s_waitcnt lgkmcnt(0)
	v_mfma_f32_16x16x32_bf16 v[28:31], v[136:139], v[132:135], v[28:31]
	v_mfma_f32_16x16x32_bf16 v[24:27], v[140:143], v[132:135], v[24:27]
	v_mfma_f32_16x16x32_bf16 v[20:23], v[148:151], v[132:135], v[20:23]
	v_mfma_f32_16x16x32_bf16 v[16:19], v[144:147], v[132:135], v[16:19]
	ds_read_b128 v[136:139], v168 offset:18432
	ds_read_b128 v[140:143], v168 offset:19968
	ds_read_b128 v[144:147], v168 offset:21504
	ds_read_b128 v[148:151], v168 offset:23040
	s_waitcnt lgkmcnt(3)
	v_mfma_f32_16x16x32_bf16 v[104:107], v[136:139], v[162:165], v[104:107]
	s_waitcnt lgkmcnt(2)
	v_mfma_f32_16x16x32_bf16 v[96:99], v[140:143], v[162:165], v[96:99]
	s_waitcnt lgkmcnt(1)
	v_mfma_f32_16x16x32_bf16 v[92:95], v[144:147], v[162:165], v[92:95]
	s_waitcnt lgkmcnt(0)
	v_mfma_f32_16x16x32_bf16 v[88:91], v[148:151], v[162:165], v[88:91]
	v_mfma_f32_16x16x32_bf16 v[76:79], v[136:139], v[172:175], v[76:79]
	v_mfma_f32_16x16x32_bf16 v[72:75], v[140:143], v[172:175], v[72:75]
	v_mfma_f32_16x16x32_bf16 v[68:71], v[144:147], v[172:175], v[68:71]
	v_mfma_f32_16x16x32_bf16 v[64:67], v[148:151], v[172:175], v[64:67]
	v_mfma_f32_16x16x32_bf16 v[44:47], v[136:139], v[128:131], v[44:47]
	v_mfma_f32_16x16x32_bf16 v[40:43], v[140:143], v[128:131], v[40:43]
	v_mfma_f32_16x16x32_bf16 v[36:39], v[144:147], v[128:131], v[36:39]
	v_mfma_f32_16x16x32_bf16 v[32:35], v[148:151], v[128:131], v[32:35]
	v_mfma_f32_16x16x32_bf16 v[12:15], v[136:139], v[132:135], v[12:15]
	v_mfma_f32_16x16x32_bf16 v[8:11], v[140:143], v[132:135], v[8:11]
	v_mfma_f32_16x16x32_bf16 v[4:7], v[144:147], v[132:135], v[4:7]
	v_mfma_f32_16x16x32_bf16 v[0:3], v[148:151], v[132:135], v[0:3]
	v_or_b32_e32 v128, s3, v157
	v_add_u32_e32 v128, v128, v169
	v_ashrrev_i32_e32 v129, 31, v128
	v_or_b32_e32 v134, s2, v170
	v_lshlrev_b64 v[132:133], 13, v[128:129]
	s_cmp_gt_u32 s5, 15
	v_lshl_add_u64 v[130:131], s[60:61], 0, v[132:133]
	s_mov_b64 s[2:3], -1
	s_cselect_b64 s[0:1], -1, 0
	s_cmp_lt_u32 s5, 16
	v_lshlrev_b32_e32 v152, 1, v134
	s_barrier
	s_cbranch_scc1 .LBB0_715
	v_mul_f32_e32 v129, 0xbfb8aa3b, v124
	v_exp_f32_e32 v129, v129
	v_mul_f32_e32 v134, 0xbfb8aa3b, v125
	v_exp_f32_e32 v134, v134
	v_mul_f32_e32 v136, 0xbfb8aa3b, v127
	v_add_f32_e32 v129, 1.0, v129
	v_exp_f32_e32 v137, v136
	v_add_f32_e32 v135, 1.0, v134
	v_rcp_f32_e32 v134, v129
	v_mul_f32_e32 v129, 0xbfb8aa3b, v126
	v_exp_f32_e32 v129, v129
	v_rcp_f32_e32 v135, v135
	v_lshl_add_u64 v[138:139], v[130:131], 0, v[152:153]
	s_mov_b64 s[2:3], 0
	v_add_f32_e32 v129, 1.0, v129
	v_rcp_f32_e32 v136, v129
	v_add_f32_e32 v129, 1.0, v137
	v_rcp_f32_e32 v137, v129
	v_pk_mul_f32 v[134:135], v[124:125], v[134:135]
	v_pk_mul_f32 v[136:137], v[126:127], v[136:137]
	v_cvt_pk_bf16_f32 v134, v134, v135
	v_cvt_pk_bf16_f32 v135, v136, v137
	v_add_co_u32_e32 v136, vcc, 0xffffe000, v138
	s_nop 1
	v_addc_co_u32_e32 v137, vcc, -1, v139, vcc
	global_store_dwordx2 v[136:137], v[134:135], off
